# NSA window PV: probability row-sum as packed v_pk_add_f32 tree (8 instrs instead of 16 serial adds)
# baseline (speedup 1.0000x reference)
; #define EXP2F(x) __builtin_amdgcn_exp2f(x)
; __device__ __forceinline__ void pv64(const bf16x8 (&vq)[8], const f32x4 (&pr)[4], f32x4 (&o)[4]) {
; #pragma unroll
;   for (int hf = 0; hf < 2; ++hf) {
;     uint4 pw;
;     pw.x = pack2bf(pr[2 * hf][0], pr[2 * hf][1]); pw.y = pack2bf(pr[2 * hf][2], pr[2 * hf][3]);
;     pw.z = pack2bf(pr[2 * hf + 1][0], pr[2 * hf + 1][1]); pw.w = pack2bf(pr[2 * hf + 1][2], pr[2 * hf + 1][3]);
;     const bf16x8 pb = __builtin_bit_cast(bf16x8, pw);
; #pragma unroll
;     for (int dt = 0; dt < 4; ++dt) o[dt] = mfma16(vq[dt * 2 + hf], pb, o[dt]);
;   }
; }
; __device__ __forceinline__ void softmax_update(f32x4 (&st)[4], float& m, float& lsum, f32x4 (&o)[4]) {
;     ...
;   const float alpha = EXP2F(m - mnew);
;   float ps = 0.f;
; #pragma unroll
;   for (int kt = 0; kt < 4; ++kt)
; #pragma unroll
;     for (int r = 0; r < 4; ++r) {
;       const float pv = EXP2F(st[kt][r] - mnew);
;       st[kt][r] = pv;
;       ps += pv;
;     }
;   lsum = lsum * alpha + ps;
.LBB0_102:
	v_sub_f32_e32 v99, v99, v98
	v_exp_f32_e32 v115, v99
	v_pk_add_f32 v[100:101], v[100:101], v[98:99] op_sel_hi:[1,0] neg_lo:[0,1] neg_hi:[0,1]
	v_exp_f32_e32 v100, v100
	v_exp_f32_e32 v101, v101
	v_pk_add_f32 v[102:103], v[102:103], v[98:99] op_sel_hi:[1,0] neg_lo:[0,1] neg_hi:[0,1]
	v_exp_f32_e32 v102, v102
	v_exp_f32_e32 v103, v103
	v_pk_add_f32 v[104:105], v[104:105], v[98:99] op_sel_hi:[1,0] neg_lo:[0,1] neg_hi:[0,1]
	v_exp_f32_e32 v104, v104
	v_exp_f32_e32 v105, v105
	v_pk_add_f32 v[106:107], v[106:107], v[98:99] op_sel_hi:[1,0] neg_lo:[0,1] neg_hi:[0,1]
	v_pk_add_f32 v[216:217], v[100:101], v[102:103]
	v_exp_f32_e32 v106, v106
	v_exp_f32_e32 v107, v107
	v_pk_add_f32 v[108:109], v[108:109], v[98:99] op_sel_hi:[1,0] neg_lo:[0,1] neg_hi:[0,1]
	v_exp_f32_e32 v108, v108
	v_exp_f32_e32 v109, v109
	v_pk_add_f32 v[110:111], v[110:111], v[98:99] op_sel_hi:[1,0] neg_lo:[0,1] neg_hi:[0,1]
	v_pk_add_f32 v[218:219], v[104:105], v[106:107]
	v_exp_f32_e32 v110, v110
	v_pk_add_f32 v[112:113], v[112:113], v[98:99] op_sel_hi:[1,0] neg_lo:[0,1] neg_hi:[0,1]
	v_sub_f32_e32 v114, v114, v98
	v_exp_f32_e32 v111, v111
	v_exp_f32_e32 v112, v112
	v_exp_f32_e32 v113, v113
	v_exp_f32_e32 v114, v114
	v_pk_add_f32 v[220:221], v[108:109], v[110:111]
	v_cvt_pk_bf16_f32 v100, v115, v100
	v_cvt_pk_bf16_f32 v101, v101, v102
	v_pk_add_f32 v[222:223], v[112:113], v[114:115]
	v_cvt_pk_bf16_f32 v102, v103, v104
	v_cvt_pk_bf16_f32 v103, v105, v106
	v_pk_add_f32 v[216:217], v[216:217], v[218:219]
	v_pk_add_f32 v[220:221], v[220:221], v[222:223]
	s_waitcnt vmcnt(15)
	v_mfma_f32_16x16x32_bf16 v[24:27], v[64:67], v[100:103], v[24:27]
	v_pk_add_f32 v[216:217], v[216:217], v[220:221]
	s_waitcnt vmcnt(13)
	v_mfma_f32_16x16x32_bf16 v[20:23], v[56:59], v[100:103], v[20:23]
	v_add_f32_e32 v99, v216, v217
	v_fmac_f32_e32 v99, v97, v92
	s_waitcnt vmcnt(11)
	v_mfma_f32_16x16x32_bf16 v[16:19], v[60:63], v[100:103], v[16:19]
	v_lshlrev_b64 v[2:3], 6, v[2:3]
	s_waitcnt vmcnt(9)
	v_mfma_f32_16x16x32_bf16 v[12:15], v[48:51], v[100:103], v[12:15]
	v_cvt_pk_bf16_f32 v48, v107, v108
	v_cvt_pk_bf16_f32 v49, v109, v110
	v_cvt_pk_bf16_f32 v50, v111, v112
	v_cvt_pk_bf16_f32 v51, v113, v114
	s_nop 1
	v_mfma_f32_16x16x32_bf16 v[24:27], v[40:43], v[48:51], v[24:27]
	v_mfma_f32_16x16x32_bf16 v[20:23], v[32:35], v[48:51], v[20:23]
	v_mfma_f32_16x16x32_bf16 v[16:19], v[36:39], v[48:51], v[16:19]
	s_waitcnt vmcnt(8)
	v_mfma_f32_16x16x32_bf16 v[12:15], v[28:31], v[48:51], v[12:15]
	v_lshl_add_u64 v[2:3], v[2:3], 1, v[144:145]
	global_load_dwordx4 v[64:67], v[2:3], off
	global_load_dwordx4 v[40:43], v[2:3], off offset:1024
	global_load_dwordx4 v[56:59], v[2:3], off offset:2048
	global_load_dwordx4 v[32:35], v[2:3], off offset:3072
	v_add_co_u32_e32 v2, vcc, s33, v2
	s_nop 1
	v_addc_co_u32_e32 v3, vcc, 0, v3, vcc
	global_load_dwordx4 v[60:63], v[2:3], off
	global_load_dwordx4 v[36:39], v[2:3], off offset:1024
	global_load_dwordx4 v[48:51], v[2:3], off offset:2048
	global_load_dwordx4 v[28:31], v[2:3], off offset:3072
	v_cmp_eq_u32_e32 vcc, s11, v93
	v_add_u32_e32 v96, 64, v96
	v_add_u32_e32 v95, 64, v95
	s_or_b64 s[20:21], vcc, s[20:21]
	v_mov_b32_e32 v97, v99
	s_mov_b32 s11, s22
	s_andn2_b64 exec, exec, s[20:21]
	s_cbranch_execz .LBB0_105
